# v118 + GEMM8 and GEMM9 K-loop heads aligned to 64 bytes (.p2align 6, s_nop fill)
# baseline (speedup 1.0000x reference)
; #define PG8_STAGE(bufoff, gbase, voff) do { _Pragma("unroll") for (int _i = 0; _i < 2; ++_i) \
;         __builtin_amdgcn_global_load_lds((const unsigned*)((const char*)(gbase) + (voff)[_i]), (LAS unsigned*)(lds + (bufoff) + ldsw + _i * 8192), 16, 0, 0); } while (0)
; #define PG8_LDA(dst, b, h) do { _Pragma("unroll") for (int m = 0; m < 4; ++m) _Pragma("unroll") for (int k = 0; k < 2; ++k) dst[m][k] = *(const LAS bf16x8*)(lds + PG8_SA(b, h) + aoff + m * 2048 + k * 1024); } while (0)
; #define PG8_LDB(dst, b, h) do { _Pragma("unroll") for (int n = 0; n < 2; ++n) _Pragma("unroll") for (int k = 0; k < 2; ++k) dst[n][k] = *(const LAS bf16x8*)(lds + PG8_SB(b, h) + boff + n * 2048 + k * 1024); } while (0)
; #define PG8_MMA(ai, bj, At, Bt) do { __builtin_amdgcn_s_setprio(1); _Pragma("unroll") for (int m = 0; m < 4; ++m) _Pragma("unroll") for (int n = 0; n < 2; ++n) _Pragma("unroll") for (int k = 0; k < 2; ++k) \
;         acc[ai][bj][m][n] = __builtin_amdgcn_mfma_f32_16x16x32_bf16(Bt[n][k], At[m][k], acc[ai][bj][m][n], 0, 0, 0); __builtin_amdgcn_s_setprio(0); } while (0)
; #define PG8_WAIT_V(n) asm volatile("s_waitcnt vmcnt(" #n ")" ::: "memory")
; #define PG8_WAIT_L(n) asm volatile("s_waitcnt lgkmcnt(" #n ")" ::: "memory")
; #define PG8_BAR __builtin_amdgcn_s_barrier()
; #define PG8_SCHED __builtin_amdgcn_sched_barrier(0)
; template <int GI>
; __device__ __forceinline__ void gemm_phase(LAS unsigned char* lds, unsigned char* ws, int G, int cblk) {
;     ...
;         for (int t = 0; t < nt; t += 2) {
;             const bool last = (t == nt - 2);
;             const char* a1 = cA + (size_t)(t + 1) * kstep;
;             const char* a2 = last ? nA : cA + (size_t)(t + 2) * kstep; const char* b2 = last ? nB : cB + (size_t)(t + 2) * kstep;
;             const char* a3 = a2 + kstep; const char* b3 = b2 + kstep;
;             PG8_LDB(B0, 0, 0); PG8_LDB(B1, 0, 1); PG8_SCHED; PG8_LDA(At, 0, 0); PG8_STAGE(PG8_SA(1, 1), a1 + hstepA, voffA);
;             PG8_WAIT_V(8); PG8_WAIT_L(0); PG8_BAR; PG8_MMA(0, 0, At, B0); PG8_MMA(0, 1, At, B1); PG8_BAR; PG8_SCHED;
;             PG8_LDA(At, 0, 1); PG8_STAGE(PG8_SB(0, 0), b2, voffB); PG8_STAGE(PG8_SB(0, 1), b2 + hstepB, voffB); PG8_STAGE(PG8_SA(0, 0), a2, voffA);
;             PG8_WAIT_V(8); PG8_WAIT_L(0); PG8_BAR; PG8_MMA(1, 0, At, B0); PG8_MMA(1, 1, At, B1); PG8_BAR; PG8_SCHED;
.LBB0_819:
	s_add_u32 s40, s40, 0x80080
	s_addc_u32 s41, s41, 0
	s_add_u32 s0, s42, 0x100
	s_addc_u32 s1, s43, 0
	s_mov_b32 s17, -2
	ds_read_b128 v[156:159], v153
	ds_read_b128 v[164:167], v153 offset:1024
	ds_read_b128 v[168:171], v153 offset:2048
	ds_read_b128 v[172:175], v153 offset:3072
	ds_read_b128 v[176:179], v154
	ds_read_b128 v[180:183], v154 offset:1024
	ds_read_b128 v[184:187], v154 offset:2048
	ds_read_b128 v[192:195], v154 offset:3072
	s_add_u32 s24, s40, 0xfff80080
	s_addc_u32 s25, s41, -1
	s_cmp_eq_u32 s17, 28
	s_cselect_b32 s45, s19, s25
	s_cselect_b32 s44, s18, s24
	s_cselect_b32 s43, s21, s1
	s_cselect_b32 s42, s20, s0
	v_lshl_add_u64 v[188:189], s[40:41], 0, v[140:141]
	s_add_i32 m0, s49, 0xc000
	ds_read_b128 v[196:199], v155
	ds_read_b128 v[200:203], v155 offset:1024
	ds_read_b128 v[204:207], v155 offset:2048
	ds_read_b128 v[208:211], v155 offset:3072
	ds_read_b128 v[212:215], v155 offset:4096
	ds_read_b128 v[216:219], v155 offset:5120
	ds_read_b128 v[220:223], v155 offset:6144
	ds_read_b128 v[224:227], v155 offset:7168
	global_load_lds_dwordx4 v[188:189], off
	v_lshl_add_u64 v[188:189], s[40:41], 0, v[142:143]
	s_add_i32 m0, s49, 0xe000
	s_nop 0
	global_load_lds_dwordx4 v[188:189], off
	s_waitcnt vmcnt(8)
	s_waitcnt lgkmcnt(0)
	s_barrier
	s_setprio 1
	s_waitcnt lgkmcnt(0)
	v_mfma_f32_16x16x32_bf16 v[124:127], v[156:159], v[196:199], 0
	v_mfma_f32_16x16x32_bf16 v[120:123], v[168:171], v[196:199], 0
	v_mfma_f32_16x16x32_bf16 v[108:111], v[156:159], v[204:207], 0
	v_mfma_f32_16x16x32_bf16 v[104:107], v[168:171], v[204:207], 0
	v_mfma_f32_16x16x32_bf16 v[92:95], v[156:159], v[212:215], 0
	v_mfma_f32_16x16x32_bf16 v[88:91], v[168:171], v[212:215], 0
	v_mfma_f32_16x16x32_bf16 v[76:79], v[156:159], v[220:223], 0
	v_mfma_f32_16x16x32_bf16 v[72:75], v[168:171], v[220:223], 0
	v_mfma_f32_16x16x32_bf16 v[124:127], v[164:167], v[200:203], v[124:127]
	v_mfma_f32_16x16x32_bf16 v[120:123], v[172:175], v[200:203], v[120:123]
	v_mfma_f32_16x16x32_bf16 v[108:111], v[164:167], v[208:211], v[108:111]
	v_mfma_f32_16x16x32_bf16 v[104:107], v[172:175], v[208:211], v[104:107]
	v_mfma_f32_16x16x32_bf16 v[92:95], v[164:167], v[216:219], v[92:95]
	v_mfma_f32_16x16x32_bf16 v[88:91], v[172:175], v[216:219], v[88:91]
	v_mfma_f32_16x16x32_bf16 v[76:79], v[164:167], v[224:227], v[76:79]
	v_mfma_f32_16x16x32_bf16 v[72:75], v[172:175], v[224:227], v[72:75]
	s_setprio 0
	s_setprio 1
	v_mfma_f32_16x16x32_bf16 v[116:119], v[176:179], v[196:199], 0
	v_mfma_f32_16x16x32_bf16 v[112:115], v[184:187], v[196:199], 0
	v_mfma_f32_16x16x32_bf16 v[100:103], v[176:179], v[204:207], 0
	v_mfma_f32_16x16x32_bf16 v[96:99], v[184:187], v[204:207], 0
	v_mfma_f32_16x16x32_bf16 v[84:87], v[176:179], v[212:215], 0
	v_mfma_f32_16x16x32_bf16 v[80:83], v[184:187], v[212:215], 0
	v_mfma_f32_16x16x32_bf16 v[68:71], v[176:179], v[220:223], 0
	v_mfma_f32_16x16x32_bf16 v[64:67], v[184:187], v[220:223], 0
	v_mfma_f32_16x16x32_bf16 v[116:119], v[180:183], v[200:203], v[116:119]
	v_mfma_f32_16x16x32_bf16 v[112:115], v[192:195], v[200:203], v[112:115]
	v_mfma_f32_16x16x32_bf16 v[100:103], v[180:183], v[208:211], v[100:103]
	v_mfma_f32_16x16x32_bf16 v[96:99], v[192:195], v[208:211], v[96:99]
	v_mfma_f32_16x16x32_bf16 v[84:87], v[180:183], v[216:219], v[84:87]
	v_mfma_f32_16x16x32_bf16 v[80:83], v[192:195], v[216:219], v[80:83]
	v_mfma_f32_16x16x32_bf16 v[68:71], v[180:183], v[224:227], v[68:71]
	v_mfma_f32_16x16x32_bf16 v[64:67], v[192:195], v[224:227], v[64:67]
	s_setprio 0
	s_barrier
	s_add_i32 s24, s56, s26
	v_lshl_add_u64 v[188:189], s[42:43], 0, v[134:135]
	s_mov_b32 m0, s24
	ds_read_b128 v[196:199], v155 offset:16384
	ds_read_b128 v[200:203], v155 offset:17408
	ds_read_b128 v[204:207], v155 offset:18432
	ds_read_b128 v[208:211], v155 offset:19456
	ds_read_b128 v[212:215], v155 offset:20480
	ds_read_b128 v[216:219], v155 offset:21504
	ds_read_b128 v[220:223], v155 offset:22528
	ds_read_b128 v[224:227], v155 offset:23552
	global_load_lds_dwordx4 v[188:189], off
	s_add_i32 m0, s24, 0x2000
	s_add_u32 s24, s42, 0x80000
	v_lshl_add_u64 v[228:229], s[42:43], 0, v[130:131]
	s_addc_u32 s25, s43, 0
	s_add_i32 s33, s57, s26
	global_load_lds_dwordx4 v[228:229], off
	v_lshl_add_u64 v[230:231], s[24:25], 0, v[134:135]
	s_mov_b32 m0, s33
	v_lshl_add_u64 v[232:233], s[44:45], 0, v[132:133]
	global_load_lds_dwordx4 v[230:231], off
	v_lshl_add_u64 v[230:231], s[24:25], 0, v[130:131]
	s_add_i32 m0, s33, 0x2000
	s_nop 0
	global_load_lds_dwordx4 v[230:231], off
	v_lshl_add_u64 v[230:231], s[44:45], 0, v[136:137]
	s_mov_b32 m0, s49
	s_nop 0
	global_load_lds_dwordx4 v[230:231], off
	s_mov_b32 m0, s50
	s_nop 0
	global_load_lds_dwordx4 v[232:233], off
	s_waitcnt vmcnt(8)
	s_waitcnt lgkmcnt(0)
	s_barrier
; #define PG8_STAGE(bufoff, gbase, voff) do { _Pragma("unroll") for (int _i = 0; _i < 2; ++_i) \
;         __builtin_amdgcn_global_load_lds((const unsigned*)((const char*)(gbase) + (voff)[_i]), (LAS unsigned*)(lds + (bufoff) + ldsw + _i * 8192), 16, 0, 0); } while (0)
; #define PG8_LDA(dst, b, h) do { _Pragma("unroll") for (int m = 0; m < 4; ++m) _Pragma("unroll") for (int k = 0; k < 2; ++k) dst[m][k] = *(const LAS bf16x8*)(lds + PG8_SA(b, h) + aoff + m * 2048 + k * 1024); } while (0)
; #define PG8_LDB(dst, b, h) do { _Pragma("unroll") for (int n = 0; n < 2; ++n) _Pragma("unroll") for (int k = 0; k < 2; ++k) dst[n][k] = *(const LAS bf16x8*)(lds + PG8_SB(b, h) + boff + n * 2048 + k * 1024); } while (0)
; #define PG8_MMA(ai, bj, At, Bt) do { __builtin_amdgcn_s_setprio(1); _Pragma("unroll") for (int m = 0; m < 4; ++m) _Pragma("unroll") for (int n = 0; n < 2; ++n) _Pragma("unroll") for (int k = 0; k < 2; ++k) \
;         acc[ai][bj][m][n] = __builtin_amdgcn_mfma_f32_16x16x32_bf16(Bt[n][k], At[m][k], acc[ai][bj][m][n], 0, 0, 0); __builtin_amdgcn_s_setprio(0); } while (0)
; #define PG8_WAIT_V(n) asm volatile("s_waitcnt vmcnt(" #n ")" ::: "memory")
; #define PG8_WAIT_L(n) asm volatile("s_waitcnt lgkmcnt(" #n ")" ::: "memory")
; #define PG8_BAR __builtin_amdgcn_s_barrier()
; #define PG8_SCHED __builtin_amdgcn_sched_barrier(0)
; template <int GI>
; __device__ __forceinline__ void gemm_phase(LAS unsigned char* lds, unsigned char* ws, int G, int cblk) {
;     ...
;             PG8_WAIT_V(8); PG8_WAIT_L(0); PG8_BAR; PG8_MMA(1, 0, At, B0); PG8_MMA(1, 1, At, B1); PG8_BAR; PG8_SCHED;
;             PG8_LDB(B0, 1, 0); PG8_LDB(B1, 1, 1); PG8_SCHED; PG8_LDA(At, 1, 0); PG8_STAGE(PG8_SA(0, 1), a2 + hstepA, voffA);
;             PG8_WAIT_V(8); PG8_WAIT_L(0); PG8_BAR; PG8_MMA(0, 0, At, B0); PG8_MMA(0, 1, At, B1); PG8_BAR; PG8_SCHED;
	s_setprio 1
	s_waitcnt lgkmcnt(0)
	v_mfma_f32_16x16x32_bf16 v[60:63], v[156:159], v[196:199], 0
	v_mfma_f32_16x16x32_bf16 v[56:59], v[168:171], v[196:199], 0
	v_mfma_f32_16x16x32_bf16 v[44:47], v[156:159], v[204:207], 0
	v_mfma_f32_16x16x32_bf16 v[40:43], v[168:171], v[204:207], 0
	v_mfma_f32_16x16x32_bf16 v[28:31], v[156:159], v[212:215], 0
	v_mfma_f32_16x16x32_bf16 v[24:27], v[168:171], v[212:215], 0
	v_mfma_f32_16x16x32_bf16 v[12:15], v[156:159], v[220:223], 0
	v_mfma_f32_16x16x32_bf16 v[8:11], v[168:171], v[220:223], 0
	v_mfma_f32_16x16x32_bf16 v[60:63], v[164:167], v[200:203], v[60:63]
	v_mfma_f32_16x16x32_bf16 v[56:59], v[172:175], v[200:203], v[56:59]
	v_mfma_f32_16x16x32_bf16 v[44:47], v[164:167], v[208:211], v[44:47]
	v_mfma_f32_16x16x32_bf16 v[40:43], v[172:175], v[208:211], v[40:43]
	v_mfma_f32_16x16x32_bf16 v[28:31], v[164:167], v[216:219], v[28:31]
	v_mfma_f32_16x16x32_bf16 v[24:27], v[172:175], v[216:219], v[24:27]
	v_mfma_f32_16x16x32_bf16 v[12:15], v[164:167], v[224:227], v[12:15]
	v_mfma_f32_16x16x32_bf16 v[8:11], v[172:175], v[224:227], v[8:11]
	s_setprio 0
	s_setprio 1
	v_mfma_f32_16x16x32_bf16 v[52:55], v[176:179], v[196:199], 0
	v_mfma_f32_16x16x32_bf16 v[48:51], v[184:187], v[196:199], 0
	v_mfma_f32_16x16x32_bf16 v[36:39], v[176:179], v[204:207], 0
	v_mfma_f32_16x16x32_bf16 v[32:35], v[184:187], v[204:207], 0
	v_mfma_f32_16x16x32_bf16 v[20:23], v[176:179], v[212:215], 0
	v_mfma_f32_16x16x32_bf16 v[16:19], v[184:187], v[212:215], 0
	v_mfma_f32_16x16x32_bf16 v[4:7], v[176:179], v[220:223], 0
	v_mfma_f32_16x16x32_bf16 v[0:3], v[184:187], v[220:223], 0
	v_mfma_f32_16x16x32_bf16 v[52:55], v[180:183], v[200:203], v[52:55]
	v_mfma_f32_16x16x32_bf16 v[48:51], v[192:195], v[200:203], v[48:51]
	v_mfma_f32_16x16x32_bf16 v[36:39], v[180:183], v[208:211], v[36:39]
	v_mfma_f32_16x16x32_bf16 v[32:35], v[192:195], v[208:211], v[32:35]
	v_mfma_f32_16x16x32_bf16 v[20:23], v[180:183], v[216:219], v[20:23]
	v_mfma_f32_16x16x32_bf16 v[16:19], v[192:195], v[216:219], v[16:19]
	v_mfma_f32_16x16x32_bf16 v[4:7], v[180:183], v[224:227], v[4:7]
	v_mfma_f32_16x16x32_bf16 v[0:3], v[192:195], v[224:227], v[0:3]
	s_setprio 0
	s_barrier
	s_add_i32 s33, 0, 0x18000
	v_add_u32_e32 v161, s33, v152
	s_add_i32 s34, 0, 0x1c000
	ds_read_b128 v[156:159], v161
	ds_read_b128 v[164:167], v161 offset:1024
	ds_read_b128 v[168:171], v161 offset:2048
	ds_read_b128 v[172:175], v161 offset:3072
	v_add_u32_e32 v161, s34, v152
	ds_read_b128 v[176:179], v161
	ds_read_b128 v[180:183], v161 offset:1024
	ds_read_b128 v[184:187], v161 offset:2048
	ds_read_b128 v[192:195], v161 offset:3072
	s_add_u32 s24, s44, 0x80000
	s_addc_u32 s25, s45, 0
	s_mov_b32 m0, s51
	v_lshl_add_u64 v[234:235], s[24:25], 0, v[136:137]
	ds_read_b128 v[196:199], v155 offset:32768
	ds_read_b128 v[200:203], v155 offset:33792
	ds_read_b128 v[204:207], v155 offset:34816
	ds_read_b128 v[208:211], v155 offset:35840
	ds_read_b128 v[212:215], v155 offset:36864
	ds_read_b128 v[216:219], v155 offset:37888
	ds_read_b128 v[220:223], v155 offset:38912
	ds_read_b128 v[224:227], v155 offset:39936
	global_load_lds_dwordx4 v[234:235], off
	v_lshl_add_u64 v[234:235], s[24:25], 0, v[132:133]
	s_mov_b32 m0, s52
	s_nop 0
	global_load_lds_dwordx4 v[234:235], off
	s_waitcnt vmcnt(8)
	s_waitcnt lgkmcnt(0)
	s_barrier
	s_setprio 1
	s_waitcnt lgkmcnt(0)
	v_mfma_f32_16x16x32_bf16 v[124:127], v[156:159], v[196:199], v[124:127]
	v_mfma_f32_16x16x32_bf16 v[120:123], v[168:171], v[196:199], v[120:123]
	v_mfma_f32_16x16x32_bf16 v[108:111], v[156:159], v[204:207], v[108:111]
	v_mfma_f32_16x16x32_bf16 v[104:107], v[168:171], v[204:207], v[104:107]
	v_mfma_f32_16x16x32_bf16 v[92:95], v[156:159], v[212:215], v[92:95]
	v_mfma_f32_16x16x32_bf16 v[88:91], v[168:171], v[212:215], v[88:91]
	v_mfma_f32_16x16x32_bf16 v[76:79], v[156:159], v[220:223], v[76:79]
	v_mfma_f32_16x16x32_bf16 v[72:75], v[168:171], v[220:223], v[72:75]
	v_mfma_f32_16x16x32_bf16 v[124:127], v[164:167], v[200:203], v[124:127]
	v_mfma_f32_16x16x32_bf16 v[120:123], v[172:175], v[200:203], v[120:123]
	v_mfma_f32_16x16x32_bf16 v[108:111], v[164:167], v[208:211], v[108:111]
	v_mfma_f32_16x16x32_bf16 v[104:107], v[172:175], v[208:211], v[104:107]
	v_mfma_f32_16x16x32_bf16 v[92:95], v[164:167], v[216:219], v[92:95]
	v_mfma_f32_16x16x32_bf16 v[88:91], v[172:175], v[216:219], v[88:91]
	v_mfma_f32_16x16x32_bf16 v[76:79], v[164:167], v[224:227], v[76:79]
	v_mfma_f32_16x16x32_bf16 v[72:75], v[172:175], v[224:227], v[72:75]
	s_setprio 0
	s_setprio 1
	v_mfma_f32_16x16x32_bf16 v[116:119], v[176:179], v[196:199], v[116:119]
	v_mfma_f32_16x16x32_bf16 v[112:115], v[184:187], v[196:199], v[112:115]
	v_mfma_f32_16x16x32_bf16 v[100:103], v[176:179], v[204:207], v[100:103]
	v_mfma_f32_16x16x32_bf16 v[96:99], v[184:187], v[204:207], v[96:99]
	v_mfma_f32_16x16x32_bf16 v[84:87], v[176:179], v[212:215], v[84:87]
	v_mfma_f32_16x16x32_bf16 v[80:83], v[184:187], v[212:215], v[80:83]
	v_mfma_f32_16x16x32_bf16 v[68:71], v[176:179], v[220:223], v[68:71]
	v_mfma_f32_16x16x32_bf16 v[64:67], v[184:187], v[220:223], v[64:67]
	v_mfma_f32_16x16x32_bf16 v[116:119], v[180:183], v[200:203], v[116:119]
	v_mfma_f32_16x16x32_bf16 v[112:115], v[192:195], v[200:203], v[112:115]
	v_mfma_f32_16x16x32_bf16 v[100:103], v[180:183], v[208:211], v[100:103]
	v_mfma_f32_16x16x32_bf16 v[96:99], v[192:195], v[208:211], v[96:99]
	v_mfma_f32_16x16x32_bf16 v[84:87], v[180:183], v[216:219], v[84:87]
	v_mfma_f32_16x16x32_bf16 v[80:83], v[192:195], v[216:219], v[80:83]
	v_mfma_f32_16x16x32_bf16 v[68:71], v[180:183], v[224:227], v[68:71]
	v_mfma_f32_16x16x32_bf16 v[64:67], v[192:195], v[224:227], v[64:67]
	s_setprio 0
	s_barrier
; #define PG8_STAGE(bufoff, gbase, voff) do { _Pragma("unroll") for (int _i = 0; _i < 2; ++_i) \
;         __builtin_amdgcn_global_load_lds((const unsigned*)((const char*)(gbase) + (voff)[_i]), (LAS unsigned*)(lds + (bufoff) + ldsw + _i * 8192), 16, 0, 0); } while (0)
; #define PG8_LDA(dst, b, h) do { _Pragma("unroll") for (int m = 0; m < 4; ++m) _Pragma("unroll") for (int k = 0; k < 2; ++k) dst[m][k] = *(const LAS bf16x8*)(lds + PG8_SA(b, h) + aoff + m * 2048 + k * 1024); } while (0)
; #define PG8_MMA(ai, bj, At, Bt) do { __builtin_amdgcn_s_setprio(1); _Pragma("unroll") for (int m = 0; m < 4; ++m) _Pragma("unroll") for (int n = 0; n < 2; ++n) _Pragma("unroll") for (int k = 0; k < 2; ++k) \
;         acc[ai][bj][m][n] = __builtin_amdgcn_mfma_f32_16x16x32_bf16(Bt[n][k], At[m][k], acc[ai][bj][m][n], 0, 0, 0); __builtin_amdgcn_s_setprio(0); } while (0)
; #define PG8_WAIT_V(n) asm volatile("s_waitcnt vmcnt(" #n ")" ::: "memory")
; #define PG8_WAIT_L(n) asm volatile("s_waitcnt lgkmcnt(" #n ")" ::: "memory")
; #define PG8_BAR __builtin_amdgcn_s_barrier()
; #define PG8_SCHED __builtin_amdgcn_sched_barrier(0)
; template <int GI>
; __device__ __forceinline__ void gemm_phase(LAS unsigned char* lds, unsigned char* ws, int G, int cblk) {
;     ...
;             PG8_LDA(At, 1, 1); PG8_STAGE(PG8_SB(1, 0), b3, voffB); PG8_STAGE(PG8_SB(1, 1), b3 + hstepB, voffB); PG8_STAGE(PG8_SA(1, 0), a3, voffA);
;             PG8_WAIT_V(8); PG8_WAIT_L(0); PG8_BAR; PG8_MMA(1, 0, At, B0); PG8_MMA(1, 1, At, B1); PG8_BAR; PG8_SCHED;
;         }
	s_add_i32 s24, s33, s26
	v_lshl_add_u64 v[188:189], v[188:189], 0, s[12:13]
	s_mov_b32 m0, s24
	ds_read_b128 v[196:199], v155 offset:49152
	ds_read_b128 v[200:203], v155 offset:50176
	ds_read_b128 v[204:207], v155 offset:51200
	ds_read_b128 v[208:211], v155 offset:52224
	ds_read_b128 v[212:215], v155 offset:53248
	ds_read_b128 v[216:219], v155 offset:54272
	ds_read_b128 v[220:223], v155 offset:55296
	ds_read_b128 v[224:227], v155 offset:56320
	global_load_lds_dwordx4 v[188:189], off
	s_add_i32 m0, s24, 0x2000
	s_add_u32 s24, s42, 0x80080
	v_lshl_add_u64 v[188:189], v[228:229], 0, s[12:13]
	s_addc_u32 s25, s43, 0
	s_add_i32 s33, s34, s26
	global_load_lds_dwordx4 v[188:189], off
	v_lshl_add_u64 v[188:189], s[24:25], 0, v[134:135]
	s_mov_b32 m0, s33
	s_nop 0
	global_load_lds_dwordx4 v[188:189], off
	v_lshl_add_u64 v[188:189], s[24:25], 0, v[130:131]
	s_add_i32 m0, s33, 0x2000
	s_nop 0
	global_load_lds_dwordx4 v[188:189], off
	v_lshl_add_u64 v[188:189], v[230:231], 0, s[12:13]
	s_mov_b32 m0, s53
	s_nop 0
	global_load_lds_dwordx4 v[188:189], off
	v_lshl_add_u64 v[188:189], v[232:233], 0, s[12:13]
	s_mov_b32 m0, s55
	s_nop 0
	global_load_lds_dwordx4 v[188:189], off
	s_waitcnt vmcnt(8)
	s_waitcnt lgkmcnt(0)
	s_barrier
	s_setprio 1
	s_waitcnt lgkmcnt(0)
	v_mfma_f32_16x16x32_bf16 v[60:63], v[156:159], v[196:199], v[60:63]
	v_mfma_f32_16x16x32_bf16 v[56:59], v[168:171], v[196:199], v[56:59]
	v_mfma_f32_16x16x32_bf16 v[44:47], v[156:159], v[204:207], v[44:47]
	v_mfma_f32_16x16x32_bf16 v[40:43], v[168:171], v[204:207], v[40:43]
	v_mfma_f32_16x16x32_bf16 v[28:31], v[156:159], v[212:215], v[28:31]
	v_mfma_f32_16x16x32_bf16 v[24:27], v[168:171], v[212:215], v[24:27]
	v_mfma_f32_16x16x32_bf16 v[12:15], v[156:159], v[220:223], v[12:15]
	v_mfma_f32_16x16x32_bf16 v[8:11], v[168:171], v[220:223], v[8:11]
	v_mfma_f32_16x16x32_bf16 v[60:63], v[164:167], v[200:203], v[60:63]
	v_mfma_f32_16x16x32_bf16 v[56:59], v[172:175], v[200:203], v[56:59]
	v_mfma_f32_16x16x32_bf16 v[44:47], v[164:167], v[208:211], v[44:47]
	v_mfma_f32_16x16x32_bf16 v[40:43], v[172:175], v[208:211], v[40:43]
	v_mfma_f32_16x16x32_bf16 v[28:31], v[164:167], v[216:219], v[28:31]
	v_mfma_f32_16x16x32_bf16 v[24:27], v[172:175], v[216:219], v[24:27]
	v_mfma_f32_16x16x32_bf16 v[12:15], v[164:167], v[224:227], v[12:15]
	v_mfma_f32_16x16x32_bf16 v[8:11], v[172:175], v[224:227], v[8:11]
	s_setprio 0
	s_setprio 1
	v_mfma_f32_16x16x32_bf16 v[52:55], v[176:179], v[196:199], v[52:55]
	v_mfma_f32_16x16x32_bf16 v[48:51], v[184:187], v[196:199], v[48:51]
	v_mfma_f32_16x16x32_bf16 v[36:39], v[176:179], v[204:207], v[36:39]
	v_mfma_f32_16x16x32_bf16 v[32:35], v[184:187], v[204:207], v[32:35]
	v_mfma_f32_16x16x32_bf16 v[20:23], v[176:179], v[212:215], v[20:23]
	v_mfma_f32_16x16x32_bf16 v[16:19], v[184:187], v[212:215], v[16:19]
	v_mfma_f32_16x16x32_bf16 v[4:7], v[176:179], v[220:223], v[4:7]
	v_mfma_f32_16x16x32_bf16 v[0:3], v[184:187], v[220:223], v[0:3]
	v_mfma_f32_16x16x32_bf16 v[52:55], v[180:183], v[200:203], v[52:55]
	v_mfma_f32_16x16x32_bf16 v[48:51], v[192:195], v[200:203], v[48:51]
	v_mfma_f32_16x16x32_bf16 v[36:39], v[180:183], v[208:211], v[36:39]
	v_mfma_f32_16x16x32_bf16 v[32:35], v[192:195], v[208:211], v[32:35]
	v_mfma_f32_16x16x32_bf16 v[20:23], v[180:183], v[216:219], v[20:23]
	v_mfma_f32_16x16x32_bf16 v[16:19], v[192:195], v[216:219], v[16:19]
	v_mfma_f32_16x16x32_bf16 v[4:7], v[180:183], v[224:227], v[4:7]
	v_mfma_f32_16x16x32_bf16 v[0:3], v[192:195], v[224:227], v[0:3]
	s_setprio 0
	s_barrier
	s_add_i32 s17, s17, 2
	s_add_u32 s40, s40, 0x100
	s_addc_u32 s41, s41, 0
	s_add_u32 s0, s0, 0x100
	s_addc_u32 s1, s1, 0
	s_cmp_gt_u32 s17, 29
	s_cbranch_scc0 .LBB0_820
	s_branch .Lpeel_exit_8
	.p2align	6

; #define PG8_STAGE(bufoff, gbase, voff) do { _Pragma("unroll") for (int _i = 0; _i < 2; ++_i) \
;         __builtin_amdgcn_global_load_lds((const unsigned*)((const char*)(gbase) + (voff)[_i]), (LAS unsigned*)(lds + (bufoff) + ldsw + _i * 8192), 16, 0, 0); } while (0)
; #define PG8_LDA(dst, b, h) do { _Pragma("unroll") for (int m = 0; m < 4; ++m) _Pragma("unroll") for (int k = 0; k < 2; ++k) dst[m][k] = *(const LAS bf16x8*)(lds + PG8_SA(b, h) + aoff + m * 2048 + k * 1024); } while (0)
; #define PG8_LDB(dst, b, h) do { _Pragma("unroll") for (int n = 0; n < 2; ++n) _Pragma("unroll") for (int k = 0; k < 2; ++k) dst[n][k] = *(const LAS bf16x8*)(lds + PG8_SB(b, h) + boff + n * 2048 + k * 1024); } while (0)
; #define PG8_MMA(ai, bj, At, Bt) do { __builtin_amdgcn_s_setprio(1); _Pragma("unroll") for (int m = 0; m < 4; ++m) _Pragma("unroll") for (int n = 0; n < 2; ++n) _Pragma("unroll") for (int k = 0; k < 2; ++k) \
;         acc[ai][bj][m][n] = __builtin_amdgcn_mfma_f32_16x16x32_bf16(Bt[n][k], At[m][k], acc[ai][bj][m][n], 0, 0, 0); __builtin_amdgcn_s_setprio(0); } while (0)
; #define PG8_WAIT_V(n) asm volatile("s_waitcnt vmcnt(" #n ")" ::: "memory")
; #define PG8_WAIT_L(n) asm volatile("s_waitcnt lgkmcnt(" #n ")" ::: "memory")
; #define PG8_BAR __builtin_amdgcn_s_barrier()
; #define PG8_SCHED __builtin_amdgcn_sched_barrier(0)
; template <int GI>
; __device__ __forceinline__ void gemm_phase(LAS unsigned char* lds, unsigned char* ws, int G, int cblk) {
;     ...
;         for (int t = 0; t < nt; t += 2) {
;             const bool last = (t == nt - 2);
;             const char* a1 = cA + (size_t)(t + 1) * kstep;
;             const char* a2 = last ? nA : cA + (size_t)(t + 2) * kstep; const char* b2 = last ? nB : cB + (size_t)(t + 2) * kstep;
;             const char* a3 = a2 + kstep; const char* b3 = b2 + kstep;
;             PG8_LDB(B0, 0, 0); PG8_LDB(B1, 0, 1); PG8_SCHED; PG8_LDA(At, 0, 0); PG8_STAGE(PG8_SA(1, 1), a1 + hstepA, voffA);
;             PG8_WAIT_V(8); PG8_WAIT_L(0); PG8_BAR; PG8_MMA(0, 0, At, B0); PG8_MMA(0, 1, At, B1); PG8_BAR; PG8_SCHED;
;             PG8_LDA(At, 0, 1); PG8_STAGE(PG8_SB(0, 0), b2, voffB); PG8_STAGE(PG8_SB(0, 1), b2 + hstepB, voffB); PG8_STAGE(PG8_SA(0, 0), a2, voffA);
;             PG8_WAIT_V(8); PG8_WAIT_L(0); PG8_BAR; PG8_MMA(1, 0, At, B0); PG8_MMA(1, 1, At, B1); PG8_BAR; PG8_SCHED;
.LBB0_895:
	s_add_u32 s15, s40, 0x100
	s_addc_u32 s53, s41, 0
	s_mov_b32 s54, -2
	ds_read_b128 v[156:159], v153
	ds_read_b128 v[164:167], v153 offset:1024
	ds_read_b128 v[168:171], v153 offset:2048
	ds_read_b128 v[172:175], v153 offset:3072
	ds_read_b128 v[176:179], v154
	ds_read_b128 v[180:183], v154 offset:1024
	ds_read_b128 v[184:187], v154 offset:2048
	ds_read_b128 v[192:195], v154 offset:3072
	s_add_u32 s40, s38, 0x100
	s_addc_u32 s41, s39, 0
	s_cmpk_eq_i32 s54, 0x54
	s_cselect_b32 s45, s21, s41
	s_cselect_b32 s44, s20, s40
	s_cselect_b32 s43, s23, s53
	s_cselect_b32 s42, s22, s15
	v_lshl_add_u64 v[188:189], s[38:39], 0, v[140:141]
	s_add_i32 m0, s24, 0xc000
	ds_read_b128 v[196:199], v155
	ds_read_b128 v[200:203], v155 offset:1024
	ds_read_b128 v[204:207], v155 offset:2048
	ds_read_b128 v[208:211], v155 offset:3072
	ds_read_b128 v[212:215], v155 offset:4096
	ds_read_b128 v[216:219], v155 offset:5120
	ds_read_b128 v[220:223], v155 offset:6144
	ds_read_b128 v[224:227], v155 offset:7168
	global_load_lds_dwordx4 v[188:189], off
	v_lshl_add_u64 v[188:189], s[38:39], 0, v[142:143]
	s_add_i32 m0, s24, 0xe000
	s_nop 0
	global_load_lds_dwordx4 v[188:189], off
	s_waitcnt vmcnt(8)
	s_waitcnt lgkmcnt(0)
	s_barrier
	s_setprio 1
	s_waitcnt lgkmcnt(0)
	v_mfma_f32_16x16x32_bf16 v[124:127], v[156:159], v[196:199], 0
	v_mfma_f32_16x16x32_bf16 v[120:123], v[168:171], v[196:199], 0
	v_mfma_f32_16x16x32_bf16 v[116:119], v[156:159], v[204:207], 0
	v_mfma_f32_16x16x32_bf16 v[112:115], v[168:171], v[204:207], 0
	v_mfma_f32_16x16x32_bf16 v[100:103], v[156:159], v[212:215], 0
	v_mfma_f32_16x16x32_bf16 v[96:99], v[168:171], v[212:215], 0
	v_mfma_f32_16x16x32_bf16 v[84:87], v[156:159], v[220:223], 0
	v_mfma_f32_16x16x32_bf16 v[80:83], v[168:171], v[220:223], 0
	v_mfma_f32_16x16x32_bf16 v[124:127], v[164:167], v[200:203], v[124:127]
	v_mfma_f32_16x16x32_bf16 v[120:123], v[172:175], v[200:203], v[120:123]
	v_mfma_f32_16x16x32_bf16 v[116:119], v[164:167], v[208:211], v[116:119]
	v_mfma_f32_16x16x32_bf16 v[112:115], v[172:175], v[208:211], v[112:115]
	v_mfma_f32_16x16x32_bf16 v[100:103], v[164:167], v[216:219], v[100:103]
	v_mfma_f32_16x16x32_bf16 v[96:99], v[172:175], v[216:219], v[96:99]
	v_mfma_f32_16x16x32_bf16 v[84:87], v[164:167], v[224:227], v[84:87]
	v_mfma_f32_16x16x32_bf16 v[80:83], v[172:175], v[224:227], v[80:83]
	s_setprio 0
	s_setprio 1
	v_mfma_f32_16x16x32_bf16 v[108:111], v[176:179], v[196:199], 0
	v_mfma_f32_16x16x32_bf16 v[104:107], v[184:187], v[196:199], 0
	v_mfma_f32_16x16x32_bf16 v[92:95], v[176:179], v[204:207], 0
	v_mfma_f32_16x16x32_bf16 v[88:91], v[184:187], v[204:207], 0
	v_mfma_f32_16x16x32_bf16 v[76:79], v[176:179], v[212:215], 0
	v_mfma_f32_16x16x32_bf16 v[72:75], v[184:187], v[212:215], 0
	v_mfma_f32_16x16x32_bf16 v[68:71], v[176:179], v[220:223], 0
	v_mfma_f32_16x16x32_bf16 v[64:67], v[184:187], v[220:223], 0
	v_mfma_f32_16x16x32_bf16 v[108:111], v[180:183], v[200:203], v[108:111]
	v_mfma_f32_16x16x32_bf16 v[104:107], v[192:195], v[200:203], v[104:107]
	v_mfma_f32_16x16x32_bf16 v[92:95], v[180:183], v[208:211], v[92:95]
	v_mfma_f32_16x16x32_bf16 v[88:91], v[192:195], v[208:211], v[88:91]
	v_mfma_f32_16x16x32_bf16 v[76:79], v[180:183], v[216:219], v[76:79]
	v_mfma_f32_16x16x32_bf16 v[72:75], v[192:195], v[216:219], v[72:75]
	v_mfma_f32_16x16x32_bf16 v[68:71], v[180:183], v[224:227], v[68:71]
	v_mfma_f32_16x16x32_bf16 v[64:67], v[192:195], v[224:227], v[64:67]
	s_setprio 0
	s_barrier
	s_add_i32 s34, s50, s0
	v_lshl_add_u64 v[188:189], s[42:43], 0, v[132:133]
	s_mov_b32 m0, s34
	ds_read_b128 v[196:199], v155 offset:16384
	ds_read_b128 v[200:203], v155 offset:17408
	ds_read_b128 v[204:207], v155 offset:18432
	ds_read_b128 v[208:211], v155 offset:19456
	ds_read_b128 v[212:215], v155 offset:20480
	ds_read_b128 v[216:219], v155 offset:21504
	ds_read_b128 v[220:223], v155 offset:22528
	ds_read_b128 v[224:227], v155 offset:23552
	global_load_lds_dwordx4 v[188:189], off
	s_add_i32 m0, s34, 0x2000
	s_add_u32 s38, s42, 0x160000
	v_lshl_add_u64 v[228:229], s[42:43], 0, v[136:137]
	s_addc_u32 s39, s43, 0
	s_add_i32 s34, s51, s0
	global_load_lds_dwordx4 v[228:229], off
	v_lshl_add_u64 v[230:231], s[38:39], 0, v[132:133]
	s_mov_b32 m0, s34
	v_lshl_add_u64 v[232:233], s[44:45], 0, v[134:135]
	global_load_lds_dwordx4 v[230:231], off
	v_lshl_add_u64 v[230:231], s[38:39], 0, v[136:137]
	s_add_i32 m0, s34, 0x2000
	s_nop 0
	global_load_lds_dwordx4 v[230:231], off
	v_lshl_add_u64 v[230:231], s[44:45], 0, v[130:131]
	s_mov_b32 m0, s24
	s_nop 0
	global_load_lds_dwordx4 v[230:231], off
	s_mov_b32 m0, s25
	s_nop 0
	global_load_lds_dwordx4 v[232:233], off
	s_waitcnt vmcnt(8)
	s_waitcnt lgkmcnt(0)
	s_barrier
; #define PG8_STAGE(bufoff, gbase, voff) do { _Pragma("unroll") for (int _i = 0; _i < 2; ++_i) \
;         __builtin_amdgcn_global_load_lds((const unsigned*)((const char*)(gbase) + (voff)[_i]), (LAS unsigned*)(lds + (bufoff) + ldsw + _i * 8192), 16, 0, 0); } while (0)
; #define PG8_LDA(dst, b, h) do { _Pragma("unroll") for (int m = 0; m < 4; ++m) _Pragma("unroll") for (int k = 0; k < 2; ++k) dst[m][k] = *(const LAS bf16x8*)(lds + PG8_SA(b, h) + aoff + m * 2048 + k * 1024); } while (0)
; #define PG8_LDB(dst, b, h) do { _Pragma("unroll") for (int n = 0; n < 2; ++n) _Pragma("unroll") for (int k = 0; k < 2; ++k) dst[n][k] = *(const LAS bf16x8*)(lds + PG8_SB(b, h) + boff + n * 2048 + k * 1024); } while (0)
; #define PG8_MMA(ai, bj, At, Bt) do { __builtin_amdgcn_s_setprio(1); _Pragma("unroll") for (int m = 0; m < 4; ++m) _Pragma("unroll") for (int n = 0; n < 2; ++n) _Pragma("unroll") for (int k = 0; k < 2; ++k) \
;         acc[ai][bj][m][n] = __builtin_amdgcn_mfma_f32_16x16x32_bf16(Bt[n][k], At[m][k], acc[ai][bj][m][n], 0, 0, 0); __builtin_amdgcn_s_setprio(0); } while (0)
; #define PG8_WAIT_V(n) asm volatile("s_waitcnt vmcnt(" #n ")" ::: "memory")
; #define PG8_WAIT_L(n) asm volatile("s_waitcnt lgkmcnt(" #n ")" ::: "memory")
; #define PG8_BAR __builtin_amdgcn_s_barrier()
; #define PG8_SCHED __builtin_amdgcn_sched_barrier(0)
; template <int GI>
; __device__ __forceinline__ void gemm_phase(LAS unsigned char* lds, unsigned char* ws, int G, int cblk) {
;     ...
;             PG8_WAIT_V(8); PG8_WAIT_L(0); PG8_BAR; PG8_MMA(1, 0, At, B0); PG8_MMA(1, 1, At, B1); PG8_BAR; PG8_SCHED;
;             PG8_LDB(B0, 1, 0); PG8_LDB(B1, 1, 1); PG8_SCHED; PG8_LDA(At, 1, 0); PG8_STAGE(PG8_SA(0, 1), a2 + hstepA, voffA);
;             PG8_WAIT_V(8); PG8_WAIT_L(0); PG8_BAR; PG8_MMA(0, 0, At, B0); PG8_MMA(0, 1, At, B1); PG8_BAR; PG8_SCHED;
	s_setprio 1
	s_waitcnt lgkmcnt(0)
	v_mfma_f32_16x16x32_bf16 v[60:63], v[156:159], v[196:199], 0
	v_mfma_f32_16x16x32_bf16 v[56:59], v[168:171], v[196:199], 0
	v_mfma_f32_16x16x32_bf16 v[52:55], v[156:159], v[204:207], 0
	v_mfma_f32_16x16x32_bf16 v[48:51], v[168:171], v[204:207], 0
	v_mfma_f32_16x16x32_bf16 v[36:39], v[156:159], v[212:215], 0
	v_mfma_f32_16x16x32_bf16 v[32:35], v[168:171], v[212:215], 0
	v_mfma_f32_16x16x32_bf16 v[20:23], v[156:159], v[220:223], 0
	v_mfma_f32_16x16x32_bf16 v[16:19], v[168:171], v[220:223], 0
	v_mfma_f32_16x16x32_bf16 v[60:63], v[164:167], v[200:203], v[60:63]
	v_mfma_f32_16x16x32_bf16 v[56:59], v[172:175], v[200:203], v[56:59]
	v_mfma_f32_16x16x32_bf16 v[52:55], v[164:167], v[208:211], v[52:55]
	v_mfma_f32_16x16x32_bf16 v[48:51], v[172:175], v[208:211], v[48:51]
	v_mfma_f32_16x16x32_bf16 v[36:39], v[164:167], v[216:219], v[36:39]
	v_mfma_f32_16x16x32_bf16 v[32:35], v[172:175], v[216:219], v[32:35]
	v_mfma_f32_16x16x32_bf16 v[20:23], v[164:167], v[224:227], v[20:23]
	v_mfma_f32_16x16x32_bf16 v[16:19], v[172:175], v[224:227], v[16:19]
	s_setprio 0
	s_setprio 1
	v_mfma_f32_16x16x32_bf16 v[44:47], v[176:179], v[196:199], 0
	v_mfma_f32_16x16x32_bf16 v[40:43], v[184:187], v[196:199], 0
	v_mfma_f32_16x16x32_bf16 v[28:31], v[176:179], v[204:207], 0
	v_mfma_f32_16x16x32_bf16 v[24:27], v[184:187], v[204:207], 0
	v_mfma_f32_16x16x32_bf16 v[12:15], v[176:179], v[212:215], 0
	v_mfma_f32_16x16x32_bf16 v[8:11], v[184:187], v[212:215], 0
	v_mfma_f32_16x16x32_bf16 v[4:7], v[176:179], v[220:223], 0
	v_mfma_f32_16x16x32_bf16 v[0:3], v[184:187], v[220:223], 0
	v_mfma_f32_16x16x32_bf16 v[44:47], v[180:183], v[200:203], v[44:47]
	v_mfma_f32_16x16x32_bf16 v[40:43], v[192:195], v[200:203], v[40:43]
	v_mfma_f32_16x16x32_bf16 v[28:31], v[180:183], v[208:211], v[28:31]
	v_mfma_f32_16x16x32_bf16 v[24:27], v[192:195], v[208:211], v[24:27]
	v_mfma_f32_16x16x32_bf16 v[12:15], v[180:183], v[216:219], v[12:15]
	v_mfma_f32_16x16x32_bf16 v[8:11], v[192:195], v[216:219], v[8:11]
	v_mfma_f32_16x16x32_bf16 v[4:7], v[180:183], v[224:227], v[4:7]
	v_mfma_f32_16x16x32_bf16 v[0:3], v[192:195], v[224:227], v[0:3]
	s_setprio 0
	s_barrier
	s_add_i32 s34, 0, 0x18000
	v_add_u32_e32 v161, s34, v152
	s_add_i32 s55, 0, 0x1c000
	ds_read_b128 v[156:159], v161
	ds_read_b128 v[164:167], v161 offset:1024
	ds_read_b128 v[168:171], v161 offset:2048
	ds_read_b128 v[172:175], v161 offset:3072
	v_add_u32_e32 v161, s55, v152
	ds_read_b128 v[176:179], v161
	ds_read_b128 v[180:183], v161 offset:1024
	ds_read_b128 v[184:187], v161 offset:2048
	ds_read_b128 v[192:195], v161 offset:3072
	s_add_u32 s38, s44, 0x160000
	s_addc_u32 s39, s45, 0
	s_mov_b32 m0, s26
	v_lshl_add_u64 v[234:235], s[38:39], 0, v[130:131]
	ds_read_b128 v[196:199], v155 offset:32768
	ds_read_b128 v[200:203], v155 offset:33792
	ds_read_b128 v[204:207], v155 offset:34816
	ds_read_b128 v[208:211], v155 offset:35840
	ds_read_b128 v[212:215], v155 offset:36864
	ds_read_b128 v[216:219], v155 offset:37888
	ds_read_b128 v[220:223], v155 offset:38912
	ds_read_b128 v[224:227], v155 offset:39936
	global_load_lds_dwordx4 v[234:235], off
	v_lshl_add_u64 v[234:235], s[38:39], 0, v[134:135]
	s_mov_b32 m0, s27
	s_nop 0
	global_load_lds_dwordx4 v[234:235], off
	s_waitcnt vmcnt(8)
	s_waitcnt lgkmcnt(0)
	s_barrier
	s_setprio 1
	s_waitcnt lgkmcnt(0)
	v_mfma_f32_16x16x32_bf16 v[124:127], v[156:159], v[196:199], v[124:127]
	v_mfma_f32_16x16x32_bf16 v[120:123], v[168:171], v[196:199], v[120:123]
	v_mfma_f32_16x16x32_bf16 v[116:119], v[156:159], v[204:207], v[116:119]
	v_mfma_f32_16x16x32_bf16 v[112:115], v[168:171], v[204:207], v[112:115]
	v_mfma_f32_16x16x32_bf16 v[100:103], v[156:159], v[212:215], v[100:103]
	v_mfma_f32_16x16x32_bf16 v[96:99], v[168:171], v[212:215], v[96:99]
	v_mfma_f32_16x16x32_bf16 v[84:87], v[156:159], v[220:223], v[84:87]
	v_mfma_f32_16x16x32_bf16 v[80:83], v[168:171], v[220:223], v[80:83]
	v_mfma_f32_16x16x32_bf16 v[124:127], v[164:167], v[200:203], v[124:127]
	v_mfma_f32_16x16x32_bf16 v[120:123], v[172:175], v[200:203], v[120:123]
	v_mfma_f32_16x16x32_bf16 v[116:119], v[164:167], v[208:211], v[116:119]
	v_mfma_f32_16x16x32_bf16 v[112:115], v[172:175], v[208:211], v[112:115]
	v_mfma_f32_16x16x32_bf16 v[100:103], v[164:167], v[216:219], v[100:103]
	v_mfma_f32_16x16x32_bf16 v[96:99], v[172:175], v[216:219], v[96:99]
	v_mfma_f32_16x16x32_bf16 v[84:87], v[164:167], v[224:227], v[84:87]
	v_mfma_f32_16x16x32_bf16 v[80:83], v[172:175], v[224:227], v[80:83]
	s_setprio 0
	s_setprio 1
	v_mfma_f32_16x16x32_bf16 v[108:111], v[176:179], v[196:199], v[108:111]
	v_mfma_f32_16x16x32_bf16 v[104:107], v[184:187], v[196:199], v[104:107]
	v_mfma_f32_16x16x32_bf16 v[92:95], v[176:179], v[204:207], v[92:95]
	v_mfma_f32_16x16x32_bf16 v[88:91], v[184:187], v[204:207], v[88:91]
	v_mfma_f32_16x16x32_bf16 v[76:79], v[176:179], v[212:215], v[76:79]
	v_mfma_f32_16x16x32_bf16 v[72:75], v[184:187], v[212:215], v[72:75]
	v_mfma_f32_16x16x32_bf16 v[68:71], v[176:179], v[220:223], v[68:71]
	v_mfma_f32_16x16x32_bf16 v[64:67], v[184:187], v[220:223], v[64:67]
	v_mfma_f32_16x16x32_bf16 v[108:111], v[180:183], v[200:203], v[108:111]
	v_mfma_f32_16x16x32_bf16 v[104:107], v[192:195], v[200:203], v[104:107]
	v_mfma_f32_16x16x32_bf16 v[92:95], v[180:183], v[208:211], v[92:95]
	v_mfma_f32_16x16x32_bf16 v[88:91], v[192:195], v[208:211], v[88:91]
	v_mfma_f32_16x16x32_bf16 v[76:79], v[180:183], v[216:219], v[76:79]
	v_mfma_f32_16x16x32_bf16 v[72:75], v[192:195], v[216:219], v[72:75]
	v_mfma_f32_16x16x32_bf16 v[68:71], v[180:183], v[224:227], v[68:71]
	v_mfma_f32_16x16x32_bf16 v[64:67], v[192:195], v[224:227], v[64:67]
	s_setprio 0
	s_barrier
; #define PG8_STAGE(bufoff, gbase, voff) do { _Pragma("unroll") for (int _i = 0; _i < 2; ++_i) \
;         __builtin_amdgcn_global_load_lds((const unsigned*)((const char*)(gbase) + (voff)[_i]), (LAS unsigned*)(lds + (bufoff) + ldsw + _i * 8192), 16, 0, 0); } while (0)
; #define PG8_LDA(dst, b, h) do { _Pragma("unroll") for (int m = 0; m < 4; ++m) _Pragma("unroll") for (int k = 0; k < 2; ++k) dst[m][k] = *(const LAS bf16x8*)(lds + PG8_SA(b, h) + aoff + m * 2048 + k * 1024); } while (0)
; #define PG8_MMA(ai, bj, At, Bt) do { __builtin_amdgcn_s_setprio(1); _Pragma("unroll") for (int m = 0; m < 4; ++m) _Pragma("unroll") for (int n = 0; n < 2; ++n) _Pragma("unroll") for (int k = 0; k < 2; ++k) \
;         acc[ai][bj][m][n] = __builtin_amdgcn_mfma_f32_16x16x32_bf16(Bt[n][k], At[m][k], acc[ai][bj][m][n], 0, 0, 0); __builtin_amdgcn_s_setprio(0); } while (0)
; #define PG8_WAIT_V(n) asm volatile("s_waitcnt vmcnt(" #n ")" ::: "memory")
; #define PG8_WAIT_L(n) asm volatile("s_waitcnt lgkmcnt(" #n ")" ::: "memory")
; #define PG8_BAR __builtin_amdgcn_s_barrier()
; #define PG8_SCHED __builtin_amdgcn_sched_barrier(0)
; template <int GI>
; __device__ __forceinline__ void gemm_phase(LAS unsigned char* lds, unsigned char* ws, int G, int cblk) {
;     ...
;             PG8_LDA(At, 1, 1); PG8_STAGE(PG8_SB(1, 0), b3, voffB); PG8_STAGE(PG8_SB(1, 1), b3 + hstepB, voffB); PG8_STAGE(PG8_SA(1, 0), a3, voffA);
;             PG8_WAIT_V(8); PG8_WAIT_L(0); PG8_BAR; PG8_MMA(1, 0, At, B0); PG8_MMA(1, 1, At, B1); PG8_BAR; PG8_SCHED;
;         }
	s_add_i32 s34, s34, s0
	v_lshl_add_u64 v[188:189], v[188:189], 0, s[10:11]
	s_mov_b32 m0, s34
	ds_read_b128 v[196:199], v155 offset:49152
	ds_read_b128 v[200:203], v155 offset:50176
	ds_read_b128 v[204:207], v155 offset:51200
	ds_read_b128 v[208:211], v155 offset:52224
	ds_read_b128 v[212:215], v155 offset:53248
	ds_read_b128 v[216:219], v155 offset:54272
	ds_read_b128 v[220:223], v155 offset:55296
	ds_read_b128 v[224:227], v155 offset:56320
	global_load_lds_dwordx4 v[188:189], off
	s_add_i32 m0, s34, 0x2000
	s_add_u32 s38, s42, 0x160080
	v_lshl_add_u64 v[188:189], v[228:229], 0, s[10:11]
	s_addc_u32 s39, s43, 0
	s_add_i32 s34, s55, s0
	global_load_lds_dwordx4 v[188:189], off
	v_lshl_add_u64 v[188:189], s[38:39], 0, v[132:133]
	s_mov_b32 m0, s34
	s_nop 0
	global_load_lds_dwordx4 v[188:189], off
	v_lshl_add_u64 v[188:189], s[38:39], 0, v[136:137]
	s_add_i32 m0, s34, 0x2000
	s_nop 0
	global_load_lds_dwordx4 v[188:189], off
	v_lshl_add_u64 v[188:189], v[230:231], 0, s[10:11]
	s_mov_b32 m0, s48
	s_nop 0
	global_load_lds_dwordx4 v[188:189], off
	v_lshl_add_u64 v[188:189], v[232:233], 0, s[10:11]
	s_mov_b32 m0, s49
	s_nop 0
	global_load_lds_dwordx4 v[188:189], off
	s_waitcnt vmcnt(8)
	s_waitcnt lgkmcnt(0)
	s_barrier
	s_setprio 1
	s_waitcnt lgkmcnt(0)
	v_mfma_f32_16x16x32_bf16 v[60:63], v[156:159], v[196:199], v[60:63]
	v_mfma_f32_16x16x32_bf16 v[56:59], v[168:171], v[196:199], v[56:59]
	v_mfma_f32_16x16x32_bf16 v[52:55], v[156:159], v[204:207], v[52:55]
	v_mfma_f32_16x16x32_bf16 v[48:51], v[168:171], v[204:207], v[48:51]
	v_mfma_f32_16x16x32_bf16 v[36:39], v[156:159], v[212:215], v[36:39]
	v_mfma_f32_16x16x32_bf16 v[32:35], v[168:171], v[212:215], v[32:35]
	v_mfma_f32_16x16x32_bf16 v[20:23], v[156:159], v[220:223], v[20:23]
	v_mfma_f32_16x16x32_bf16 v[16:19], v[168:171], v[220:223], v[16:19]
	v_mfma_f32_16x16x32_bf16 v[60:63], v[164:167], v[200:203], v[60:63]
	v_mfma_f32_16x16x32_bf16 v[56:59], v[172:175], v[200:203], v[56:59]
	v_mfma_f32_16x16x32_bf16 v[52:55], v[164:167], v[208:211], v[52:55]
	v_mfma_f32_16x16x32_bf16 v[48:51], v[172:175], v[208:211], v[48:51]
	v_mfma_f32_16x16x32_bf16 v[36:39], v[164:167], v[216:219], v[36:39]
	v_mfma_f32_16x16x32_bf16 v[32:35], v[172:175], v[216:219], v[32:35]
	v_mfma_f32_16x16x32_bf16 v[20:23], v[164:167], v[224:227], v[20:23]
	v_mfma_f32_16x16x32_bf16 v[16:19], v[172:175], v[224:227], v[16:19]
	s_setprio 0
	s_setprio 1
	v_mfma_f32_16x16x32_bf16 v[44:47], v[176:179], v[196:199], v[44:47]
	v_mfma_f32_16x16x32_bf16 v[40:43], v[184:187], v[196:199], v[40:43]
	v_mfma_f32_16x16x32_bf16 v[28:31], v[176:179], v[204:207], v[28:31]
	v_mfma_f32_16x16x32_bf16 v[24:27], v[184:187], v[204:207], v[24:27]
	v_mfma_f32_16x16x32_bf16 v[12:15], v[176:179], v[212:215], v[12:15]
	v_mfma_f32_16x16x32_bf16 v[8:11], v[184:187], v[212:215], v[8:11]
	v_mfma_f32_16x16x32_bf16 v[4:7], v[176:179], v[220:223], v[4:7]
	v_mfma_f32_16x16x32_bf16 v[0:3], v[184:187], v[220:223], v[0:3]
	v_mfma_f32_16x16x32_bf16 v[44:47], v[180:183], v[200:203], v[44:47]
	v_mfma_f32_16x16x32_bf16 v[40:43], v[192:195], v[200:203], v[40:43]
	v_mfma_f32_16x16x32_bf16 v[28:31], v[180:183], v[208:211], v[28:31]
	v_mfma_f32_16x16x32_bf16 v[24:27], v[192:195], v[208:211], v[24:27]
	v_mfma_f32_16x16x32_bf16 v[12:15], v[180:183], v[216:219], v[12:15]
	v_mfma_f32_16x16x32_bf16 v[8:11], v[192:195], v[216:219], v[8:11]
	v_mfma_f32_16x16x32_bf16 v[4:7], v[180:183], v[224:227], v[4:7]
	v_mfma_f32_16x16x32_bf16 v[0:3], v[192:195], v[224:227], v[0:3]
	s_setprio 0
	s_barrier
	s_add_i32 s54, s54, 2
	s_add_u32 s15, s15, 0x100
	s_addc_u32 s53, s53, 0
	s_cmpk_gt_u32 s54, 0x55
	s_mov_b64 s[38:39], s[40:41]
	s_cbranch_scc0 .LBB0_896
	s_branch .Lpeel_exit_9
	.p2align	6
